# bound clamp + SWRITE address sharing via immediate offsets
# baseline (speedup 1.0000x reference)
; __device__ __forceinline__ void phase_attn(const Params& p, int l, unsigned char* shm) {
;   const bf16_t* qkv = (const bf16_t*)(p.ws + WS_QKV); const bf16_t* gates = (const bf16_t*)(p.ws + WS_GATES);
;   bf16_t* merged = (bf16_t*)(p.ws + WS_XN);
;   const float* lutall = (const float*)(p.ws + WS_LUT); const float* lamp = (const float*)(p.ws + WS_LAM);
;   AttnEpi E; E.park = (float*)(p.ws + WS_PARK) + (size_t)blockIdx.x * 65536; E.gsub = p.in[22] + l * 128; E.lam = lamp[2 * l]; E.oml = lamp[2 * l + 1];
.LBB0_70:
	s_and_b64 vcc, exec, s[0:1]
	s_cbranch_vccz .LBB0_214
	v_readlane_b32 s0, v252, 49
	v_readlane_b32 s1, v252, 50
	s_andn2_b64 vcc, exec, s[0:1]
	s_cbranch_vccnz .LBB0_213
	v_readlane_b32 s12, v254, 63
	v_readlane_b32 s16, v254, 31
	v_readlane_b32 s17, v254, 32
	v_readlane_b32 s18, v254, 33
	v_readlane_b32 s19, v254, 34
	v_readlane_b32 s20, v254, 39
	v_readlane_b32 s21, v254, 40
	v_readlane_b32 s22, v254, 41
	v_readlane_b32 s23, v254, 42
	s_nop 3
	s_lshl_b32 s28, s12, 9
	s_add_u32 s16, s16, s28
	s_addc_u32 s17, s17, 0
	s_add_u32 s18, s18, s28
	s_addc_u32 s19, s19, 0
	s_lshl_b32 s28, s12, 8
	s_add_u32 s20, s20, s28
	s_addc_u32 s21, s21, 0
	s_add_u32 s22, s22, s28
	s_addc_u32 s23, s23, 0
	s_mov_b32 s24, 0
	s_mov_b32 s25, 0
	s_mov_b32 s26, 0
	s_mov_b32 s27, 0
	s_load_dwordx16 s[52:67], s[16:17], 0x0
	s_waitcnt lgkmcnt(0)
	s_and_b32 s28, s52, 0x7fffffff
	s_max_u32 s24, s24, s28
	s_and_b32 s28, s53, 0x7fffffff
	s_max_u32 s24, s24, s28
	s_and_b32 s28, s54, 0x7fffffff
	s_max_u32 s24, s24, s28
	s_and_b32 s28, s55, 0x7fffffff
	s_max_u32 s24, s24, s28
	s_and_b32 s28, s56, 0x7fffffff
	s_max_u32 s24, s24, s28
	s_and_b32 s28, s57, 0x7fffffff
	s_max_u32 s24, s24, s28
	s_and_b32 s28, s58, 0x7fffffff
	s_max_u32 s24, s24, s28
	s_and_b32 s28, s59, 0x7fffffff
	s_max_u32 s24, s24, s28
	s_and_b32 s28, s60, 0x7fffffff
	s_max_u32 s24, s24, s28
	s_and_b32 s28, s61, 0x7fffffff
	s_max_u32 s24, s24, s28
	s_and_b32 s28, s62, 0x7fffffff
	s_max_u32 s24, s24, s28
	s_and_b32 s28, s63, 0x7fffffff
	s_max_u32 s24, s24, s28
	s_and_b32 s28, s64, 0x7fffffff
	s_max_u32 s24, s24, s28
	s_and_b32 s28, s65, 0x7fffffff
	s_max_u32 s24, s24, s28
	s_and_b32 s28, s66, 0x7fffffff
	s_max_u32 s24, s24, s28
	s_and_b32 s28, s67, 0x7fffffff
	s_max_u32 s24, s24, s28
	s_load_dwordx16 s[52:67], s[16:17], 0x40
	s_waitcnt lgkmcnt(0)
	s_and_b32 s28, s52, 0x7fffffff
	s_max_u32 s24, s24, s28
	s_and_b32 s28, s53, 0x7fffffff
	s_max_u32 s24, s24, s28
	s_and_b32 s28, s54, 0x7fffffff
	s_max_u32 s24, s24, s28
	s_and_b32 s28, s55, 0x7fffffff
	s_max_u32 s24, s24, s28
	s_and_b32 s28, s56, 0x7fffffff
	s_max_u32 s24, s24, s28
	s_and_b32 s28, s57, 0x7fffffff
	s_max_u32 s24, s24, s28
	s_and_b32 s28, s58, 0x7fffffff
	s_max_u32 s24, s24, s28
	s_and_b32 s28, s59, 0x7fffffff
	s_max_u32 s24, s24, s28
	s_and_b32 s28, s60, 0x7fffffff
	s_max_u32 s24, s24, s28
	s_and_b32 s28, s61, 0x7fffffff
	s_max_u32 s24, s24, s28
	s_and_b32 s28, s62, 0x7fffffff
	s_max_u32 s24, s24, s28
	s_and_b32 s28, s63, 0x7fffffff
	s_max_u32 s24, s24, s28
	s_and_b32 s28, s64, 0x7fffffff
	s_max_u32 s24, s24, s28
	s_and_b32 s28, s65, 0x7fffffff
	s_max_u32 s24, s24, s28
	s_and_b32 s28, s66, 0x7fffffff
	s_max_u32 s24, s24, s28
	s_and_b32 s28, s67, 0x7fffffff
	s_max_u32 s24, s24, s28
	s_load_dwordx16 s[52:67], s[16:17], 0x80
	s_waitcnt lgkmcnt(0)
	s_and_b32 s28, s52, 0x7fffffff
	s_max_u32 s24, s24, s28
	s_and_b32 s28, s53, 0x7fffffff
	s_max_u32 s24, s24, s28
	s_and_b32 s28, s54, 0x7fffffff
	s_max_u32 s24, s24, s28
	s_and_b32 s28, s55, 0x7fffffff
	s_max_u32 s24, s24, s28
	s_and_b32 s28, s56, 0x7fffffff
	s_max_u32 s24, s24, s28
	s_and_b32 s28, s57, 0x7fffffff
	s_max_u32 s24, s24, s28
	s_and_b32 s28, s58, 0x7fffffff
	s_max_u32 s24, s24, s28
	s_and_b32 s28, s59, 0x7fffffff
	s_max_u32 s24, s24, s28
	s_and_b32 s28, s60, 0x7fffffff
	s_max_u32 s24, s24, s28
	s_and_b32 s28, s61, 0x7fffffff
	s_max_u32 s24, s24, s28
	s_and_b32 s28, s62, 0x7fffffff
	s_max_u32 s24, s24, s28
	s_and_b32 s28, s63, 0x7fffffff
	s_max_u32 s24, s24, s28
	s_and_b32 s28, s64, 0x7fffffff
	s_max_u32 s24, s24, s28
	s_and_b32 s28, s65, 0x7fffffff
	s_max_u32 s24, s24, s28
	s_and_b32 s28, s66, 0x7fffffff
	s_max_u32 s24, s24, s28
	s_and_b32 s28, s67, 0x7fffffff
	s_max_u32 s24, s24, s28
	s_load_dwordx16 s[52:67], s[16:17], 0xc0
	s_waitcnt lgkmcnt(0)
	s_and_b32 s28, s52, 0x7fffffff
	s_max_u32 s24, s24, s28
	s_and_b32 s28, s53, 0x7fffffff
	s_max_u32 s24, s24, s28
	s_and_b32 s28, s54, 0x7fffffff
	s_max_u32 s24, s24, s28
	s_and_b32 s28, s55, 0x7fffffff
	s_max_u32 s24, s24, s28
	s_and_b32 s28, s56, 0x7fffffff
	s_max_u32 s24, s24, s28
	s_and_b32 s28, s57, 0x7fffffff
	s_max_u32 s24, s24, s28
	s_and_b32 s28, s58, 0x7fffffff
	s_max_u32 s24, s24, s28
	s_and_b32 s28, s59, 0x7fffffff
	s_max_u32 s24, s24, s28
	s_and_b32 s28, s60, 0x7fffffff
	s_max_u32 s24, s24, s28
	s_and_b32 s28, s61, 0x7fffffff
	s_max_u32 s24, s24, s28
	s_and_b32 s28, s62, 0x7fffffff
	s_max_u32 s24, s24, s28
	s_and_b32 s28, s63, 0x7fffffff
	s_max_u32 s24, s24, s28
	s_and_b32 s28, s64, 0x7fffffff
	s_max_u32 s24, s24, s28
	s_and_b32 s28, s65, 0x7fffffff
	s_max_u32 s24, s24, s28
	s_and_b32 s28, s66, 0x7fffffff
	s_max_u32 s24, s24, s28
	s_and_b32 s28, s67, 0x7fffffff
	s_max_u32 s24, s24, s28
	s_load_dwordx16 s[52:67], s[16:17], 0x100
	s_waitcnt lgkmcnt(0)
	s_and_b32 s28, s52, 0x7fffffff
	s_max_u32 s24, s24, s28
	s_and_b32 s28, s53, 0x7fffffff
	s_max_u32 s24, s24, s28
	s_and_b32 s28, s54, 0x7fffffff
	s_max_u32 s24, s24, s28
	s_and_b32 s28, s55, 0x7fffffff
	s_max_u32 s24, s24, s28
	s_and_b32 s28, s56, 0x7fffffff
	s_max_u32 s24, s24, s28
	s_and_b32 s28, s57, 0x7fffffff
	s_max_u32 s24, s24, s28
	s_and_b32 s28, s58, 0x7fffffff
	s_max_u32 s24, s24, s28
	s_and_b32 s28, s59, 0x7fffffff
	s_max_u32 s24, s24, s28
	s_and_b32 s28, s60, 0x7fffffff
	s_max_u32 s24, s24, s28
	s_and_b32 s28, s61, 0x7fffffff
	s_max_u32 s24, s24, s28
	s_and_b32 s28, s62, 0x7fffffff
	s_max_u32 s24, s24, s28
	s_and_b32 s28, s63, 0x7fffffff
	s_max_u32 s24, s24, s28
	s_and_b32 s28, s64, 0x7fffffff
	s_max_u32 s24, s24, s28
	s_and_b32 s28, s65, 0x7fffffff
	s_max_u32 s24, s24, s28
	s_and_b32 s28, s66, 0x7fffffff
	s_max_u32 s24, s24, s28
	s_and_b32 s28, s67, 0x7fffffff
	s_max_u32 s24, s24, s28
	s_load_dwordx16 s[52:67], s[16:17], 0x140
	s_waitcnt lgkmcnt(0)
; __device__ __forceinline__ void phase_attn(const Params& p, int l, unsigned char* shm) {
;   const bf16_t* qkv = (const bf16_t*)(p.ws + WS_QKV); const bf16_t* gates = (const bf16_t*)(p.ws + WS_GATES);
;   bf16_t* merged = (bf16_t*)(p.ws + WS_XN);
;   const float* lutall = (const float*)(p.ws + WS_LUT); const float* lamp = (const float*)(p.ws + WS_LAM);
;   AttnEpi E; E.park = (float*)(p.ws + WS_PARK) + (size_t)blockIdx.x * 65536; E.gsub = p.in[22] + l * 128; E.lam = lamp[2 * l]; E.oml = lamp[2 * l + 1];
	s_and_b32 s28, s52, 0x7fffffff
	s_max_u32 s24, s24, s28
	s_and_b32 s28, s53, 0x7fffffff
	s_max_u32 s24, s24, s28
	s_and_b32 s28, s54, 0x7fffffff
	s_max_u32 s24, s24, s28
	s_and_b32 s28, s55, 0x7fffffff
	s_max_u32 s24, s24, s28
	s_and_b32 s28, s56, 0x7fffffff
	s_max_u32 s24, s24, s28
	s_and_b32 s28, s57, 0x7fffffff
	s_max_u32 s24, s24, s28
	s_and_b32 s28, s58, 0x7fffffff
	s_max_u32 s24, s24, s28
	s_and_b32 s28, s59, 0x7fffffff
	s_max_u32 s24, s24, s28
	s_and_b32 s28, s60, 0x7fffffff
	s_max_u32 s24, s24, s28
	s_and_b32 s28, s61, 0x7fffffff
	s_max_u32 s24, s24, s28
	s_and_b32 s28, s62, 0x7fffffff
	s_max_u32 s24, s24, s28
	s_and_b32 s28, s63, 0x7fffffff
	s_max_u32 s24, s24, s28
	s_and_b32 s28, s64, 0x7fffffff
	s_max_u32 s24, s24, s28
	s_and_b32 s28, s65, 0x7fffffff
	s_max_u32 s24, s24, s28
	s_and_b32 s28, s66, 0x7fffffff
	s_max_u32 s24, s24, s28
	s_and_b32 s28, s67, 0x7fffffff
	s_max_u32 s24, s24, s28
	s_load_dwordx16 s[52:67], s[16:17], 0x180
	s_waitcnt lgkmcnt(0)
	s_and_b32 s28, s52, 0x7fffffff
	s_max_u32 s24, s24, s28
	s_and_b32 s28, s53, 0x7fffffff
	s_max_u32 s24, s24, s28
	s_and_b32 s28, s54, 0x7fffffff
	s_max_u32 s24, s24, s28
	s_and_b32 s28, s55, 0x7fffffff
	s_max_u32 s24, s24, s28
	s_and_b32 s28, s56, 0x7fffffff
	s_max_u32 s24, s24, s28
	s_and_b32 s28, s57, 0x7fffffff
	s_max_u32 s24, s24, s28
	s_and_b32 s28, s58, 0x7fffffff
	s_max_u32 s24, s24, s28
	s_and_b32 s28, s59, 0x7fffffff
	s_max_u32 s24, s24, s28
	s_and_b32 s28, s60, 0x7fffffff
	s_max_u32 s24, s24, s28
	s_and_b32 s28, s61, 0x7fffffff
	s_max_u32 s24, s24, s28
	s_and_b32 s28, s62, 0x7fffffff
	s_max_u32 s24, s24, s28
	s_and_b32 s28, s63, 0x7fffffff
	s_max_u32 s24, s24, s28
	s_and_b32 s28, s64, 0x7fffffff
	s_max_u32 s24, s24, s28
	s_and_b32 s28, s65, 0x7fffffff
	s_max_u32 s24, s24, s28
	s_and_b32 s28, s66, 0x7fffffff
	s_max_u32 s24, s24, s28
	s_and_b32 s28, s67, 0x7fffffff
	s_max_u32 s24, s24, s28
	s_load_dwordx16 s[52:67], s[16:17], 0x1c0
	s_waitcnt lgkmcnt(0)
	s_and_b32 s28, s52, 0x7fffffff
	s_max_u32 s24, s24, s28
	s_and_b32 s28, s53, 0x7fffffff
	s_max_u32 s24, s24, s28
	s_and_b32 s28, s54, 0x7fffffff
	s_max_u32 s24, s24, s28
	s_and_b32 s28, s55, 0x7fffffff
	s_max_u32 s24, s24, s28
	s_and_b32 s28, s56, 0x7fffffff
	s_max_u32 s24, s24, s28
	s_and_b32 s28, s57, 0x7fffffff
	s_max_u32 s24, s24, s28
	s_and_b32 s28, s58, 0x7fffffff
	s_max_u32 s24, s24, s28
	s_and_b32 s28, s59, 0x7fffffff
	s_max_u32 s24, s24, s28
	s_and_b32 s28, s60, 0x7fffffff
	s_max_u32 s24, s24, s28
	s_and_b32 s28, s61, 0x7fffffff
	s_max_u32 s24, s24, s28
	s_and_b32 s28, s62, 0x7fffffff
	s_max_u32 s24, s24, s28
	s_and_b32 s28, s63, 0x7fffffff
	s_max_u32 s24, s24, s28
	s_and_b32 s28, s64, 0x7fffffff
	s_max_u32 s24, s24, s28
	s_and_b32 s28, s65, 0x7fffffff
	s_max_u32 s24, s24, s28
	s_and_b32 s28, s66, 0x7fffffff
	s_max_u32 s24, s24, s28
	s_and_b32 s28, s67, 0x7fffffff
	s_max_u32 s24, s24, s28
	s_load_dwordx16 s[52:67], s[18:19], 0x0
	s_waitcnt lgkmcnt(0)
	s_and_b32 s28, s52, 0x7fffffff
	s_max_u32 s25, s25, s28
	s_and_b32 s28, s53, 0x7fffffff
	s_max_u32 s25, s25, s28
	s_and_b32 s28, s54, 0x7fffffff
	s_max_u32 s25, s25, s28
	s_and_b32 s28, s55, 0x7fffffff
	s_max_u32 s25, s25, s28
	s_and_b32 s28, s56, 0x7fffffff
	s_max_u32 s25, s25, s28
	s_and_b32 s28, s57, 0x7fffffff
	s_max_u32 s25, s25, s28
	s_and_b32 s28, s58, 0x7fffffff
	s_max_u32 s25, s25, s28
	s_and_b32 s28, s59, 0x7fffffff
	s_max_u32 s25, s25, s28
	s_and_b32 s28, s60, 0x7fffffff
	s_max_u32 s25, s25, s28
	s_and_b32 s28, s61, 0x7fffffff
	s_max_u32 s25, s25, s28
	s_and_b32 s28, s62, 0x7fffffff
	s_max_u32 s25, s25, s28
	s_and_b32 s28, s63, 0x7fffffff
	s_max_u32 s25, s25, s28
	s_and_b32 s28, s64, 0x7fffffff
	s_max_u32 s25, s25, s28
	s_and_b32 s28, s65, 0x7fffffff
	s_max_u32 s25, s25, s28
	s_and_b32 s28, s66, 0x7fffffff
	s_max_u32 s25, s25, s28
	s_and_b32 s28, s67, 0x7fffffff
	s_max_u32 s25, s25, s28
	s_load_dwordx16 s[52:67], s[18:19], 0x40
	s_waitcnt lgkmcnt(0)
	s_and_b32 s28, s52, 0x7fffffff
	s_max_u32 s25, s25, s28
	s_and_b32 s28, s53, 0x7fffffff
	s_max_u32 s25, s25, s28
	s_and_b32 s28, s54, 0x7fffffff
	s_max_u32 s25, s25, s28
	s_and_b32 s28, s55, 0x7fffffff
	s_max_u32 s25, s25, s28
	s_and_b32 s28, s56, 0x7fffffff
	s_max_u32 s25, s25, s28
	s_and_b32 s28, s57, 0x7fffffff
	s_max_u32 s25, s25, s28
	s_and_b32 s28, s58, 0x7fffffff
	s_max_u32 s25, s25, s28
	s_and_b32 s28, s59, 0x7fffffff
	s_max_u32 s25, s25, s28
	s_and_b32 s28, s60, 0x7fffffff
	s_max_u32 s25, s25, s28
	s_and_b32 s28, s61, 0x7fffffff
	s_max_u32 s25, s25, s28
	s_and_b32 s28, s62, 0x7fffffff
	s_max_u32 s25, s25, s28
	s_and_b32 s28, s63, 0x7fffffff
	s_max_u32 s25, s25, s28
	s_and_b32 s28, s64, 0x7fffffff
	s_max_u32 s25, s25, s28
	s_and_b32 s28, s65, 0x7fffffff
	s_max_u32 s25, s25, s28
	s_and_b32 s28, s66, 0x7fffffff
	s_max_u32 s25, s25, s28
	s_and_b32 s28, s67, 0x7fffffff
	s_max_u32 s25, s25, s28
	s_load_dwordx16 s[52:67], s[18:19], 0x80
	s_waitcnt lgkmcnt(0)
	s_and_b32 s28, s52, 0x7fffffff
	s_max_u32 s25, s25, s28
	s_and_b32 s28, s53, 0x7fffffff
	s_max_u32 s25, s25, s28
	s_and_b32 s28, s54, 0x7fffffff
	s_max_u32 s25, s25, s28
	s_and_b32 s28, s55, 0x7fffffff
	s_max_u32 s25, s25, s28
	s_and_b32 s28, s56, 0x7fffffff
	s_max_u32 s25, s25, s28
	s_and_b32 s28, s57, 0x7fffffff
	s_max_u32 s25, s25, s28
	s_and_b32 s28, s58, 0x7fffffff
	s_max_u32 s25, s25, s28
	s_and_b32 s28, s59, 0x7fffffff
	s_max_u32 s25, s25, s28
	s_and_b32 s28, s60, 0x7fffffff
	s_max_u32 s25, s25, s28
	s_and_b32 s28, s61, 0x7fffffff
	s_max_u32 s25, s25, s28
	s_and_b32 s28, s62, 0x7fffffff
	s_max_u32 s25, s25, s28
	s_and_b32 s28, s63, 0x7fffffff
	s_max_u32 s25, s25, s28
	s_and_b32 s28, s64, 0x7fffffff
	s_max_u32 s25, s25, s28
	s_and_b32 s28, s65, 0x7fffffff
	s_max_u32 s25, s25, s28
	s_and_b32 s28, s66, 0x7fffffff
	s_max_u32 s25, s25, s28
	s_and_b32 s28, s67, 0x7fffffff
	s_max_u32 s25, s25, s28
	s_load_dwordx16 s[52:67], s[18:19], 0xc0
	s_waitcnt lgkmcnt(0)
; __device__ __forceinline__ void phase_attn(const Params& p, int l, unsigned char* shm) {
;   const bf16_t* qkv = (const bf16_t*)(p.ws + WS_QKV); const bf16_t* gates = (const bf16_t*)(p.ws + WS_GATES);
;   bf16_t* merged = (bf16_t*)(p.ws + WS_XN);
;   const float* lutall = (const float*)(p.ws + WS_LUT); const float* lamp = (const float*)(p.ws + WS_LAM);
;   AttnEpi E; E.park = (float*)(p.ws + WS_PARK) + (size_t)blockIdx.x * 65536; E.gsub = p.in[22] + l * 128; E.lam = lamp[2 * l]; E.oml = lamp[2 * l + 1];
	s_and_b32 s28, s52, 0x7fffffff
	s_max_u32 s25, s25, s28
	s_and_b32 s28, s53, 0x7fffffff
	s_max_u32 s25, s25, s28
	s_and_b32 s28, s54, 0x7fffffff
	s_max_u32 s25, s25, s28
	s_and_b32 s28, s55, 0x7fffffff
	s_max_u32 s25, s25, s28
	s_and_b32 s28, s56, 0x7fffffff
	s_max_u32 s25, s25, s28
	s_and_b32 s28, s57, 0x7fffffff
	s_max_u32 s25, s25, s28
	s_and_b32 s28, s58, 0x7fffffff
	s_max_u32 s25, s25, s28
	s_and_b32 s28, s59, 0x7fffffff
	s_max_u32 s25, s25, s28
	s_and_b32 s28, s60, 0x7fffffff
	s_max_u32 s25, s25, s28
	s_and_b32 s28, s61, 0x7fffffff
	s_max_u32 s25, s25, s28
	s_and_b32 s28, s62, 0x7fffffff
	s_max_u32 s25, s25, s28
	s_and_b32 s28, s63, 0x7fffffff
	s_max_u32 s25, s25, s28
	s_and_b32 s28, s64, 0x7fffffff
	s_max_u32 s25, s25, s28
	s_and_b32 s28, s65, 0x7fffffff
	s_max_u32 s25, s25, s28
	s_and_b32 s28, s66, 0x7fffffff
	s_max_u32 s25, s25, s28
	s_and_b32 s28, s67, 0x7fffffff
	s_max_u32 s25, s25, s28
	s_load_dwordx16 s[52:67], s[18:19], 0x100
	s_waitcnt lgkmcnt(0)
	s_and_b32 s28, s52, 0x7fffffff
	s_max_u32 s25, s25, s28
	s_and_b32 s28, s53, 0x7fffffff
	s_max_u32 s25, s25, s28
	s_and_b32 s28, s54, 0x7fffffff
	s_max_u32 s25, s25, s28
	s_and_b32 s28, s55, 0x7fffffff
	s_max_u32 s25, s25, s28
	s_and_b32 s28, s56, 0x7fffffff
	s_max_u32 s25, s25, s28
	s_and_b32 s28, s57, 0x7fffffff
	s_max_u32 s25, s25, s28
	s_and_b32 s28, s58, 0x7fffffff
	s_max_u32 s25, s25, s28
	s_and_b32 s28, s59, 0x7fffffff
	s_max_u32 s25, s25, s28
	s_and_b32 s28, s60, 0x7fffffff
	s_max_u32 s25, s25, s28
	s_and_b32 s28, s61, 0x7fffffff
	s_max_u32 s25, s25, s28
	s_and_b32 s28, s62, 0x7fffffff
	s_max_u32 s25, s25, s28
	s_and_b32 s28, s63, 0x7fffffff
	s_max_u32 s25, s25, s28
	s_and_b32 s28, s64, 0x7fffffff
	s_max_u32 s25, s25, s28
	s_and_b32 s28, s65, 0x7fffffff
	s_max_u32 s25, s25, s28
	s_and_b32 s28, s66, 0x7fffffff
	s_max_u32 s25, s25, s28
	s_and_b32 s28, s67, 0x7fffffff
	s_max_u32 s25, s25, s28
	s_load_dwordx16 s[52:67], s[18:19], 0x140
	s_waitcnt lgkmcnt(0)
	s_and_b32 s28, s52, 0x7fffffff
	s_max_u32 s25, s25, s28
	s_and_b32 s28, s53, 0x7fffffff
	s_max_u32 s25, s25, s28
	s_and_b32 s28, s54, 0x7fffffff
	s_max_u32 s25, s25, s28
	s_and_b32 s28, s55, 0x7fffffff
	s_max_u32 s25, s25, s28
	s_and_b32 s28, s56, 0x7fffffff
	s_max_u32 s25, s25, s28
	s_and_b32 s28, s57, 0x7fffffff
	s_max_u32 s25, s25, s28
	s_and_b32 s28, s58, 0x7fffffff
	s_max_u32 s25, s25, s28
	s_and_b32 s28, s59, 0x7fffffff
	s_max_u32 s25, s25, s28
	s_and_b32 s28, s60, 0x7fffffff
	s_max_u32 s25, s25, s28
	s_and_b32 s28, s61, 0x7fffffff
	s_max_u32 s25, s25, s28
	s_and_b32 s28, s62, 0x7fffffff
	s_max_u32 s25, s25, s28
	s_and_b32 s28, s63, 0x7fffffff
	s_max_u32 s25, s25, s28
	s_and_b32 s28, s64, 0x7fffffff
	s_max_u32 s25, s25, s28
	s_and_b32 s28, s65, 0x7fffffff
	s_max_u32 s25, s25, s28
	s_and_b32 s28, s66, 0x7fffffff
	s_max_u32 s25, s25, s28
	s_and_b32 s28, s67, 0x7fffffff
	s_max_u32 s25, s25, s28
	s_load_dwordx16 s[52:67], s[18:19], 0x180
	s_waitcnt lgkmcnt(0)
	s_and_b32 s28, s52, 0x7fffffff
	s_max_u32 s25, s25, s28
	s_and_b32 s28, s53, 0x7fffffff
	s_max_u32 s25, s25, s28
	s_and_b32 s28, s54, 0x7fffffff
	s_max_u32 s25, s25, s28
	s_and_b32 s28, s55, 0x7fffffff
	s_max_u32 s25, s25, s28
	s_and_b32 s28, s56, 0x7fffffff
	s_max_u32 s25, s25, s28
	s_and_b32 s28, s57, 0x7fffffff
	s_max_u32 s25, s25, s28
	s_and_b32 s28, s58, 0x7fffffff
	s_max_u32 s25, s25, s28
	s_and_b32 s28, s59, 0x7fffffff
	s_max_u32 s25, s25, s28
	s_and_b32 s28, s60, 0x7fffffff
	s_max_u32 s25, s25, s28
	s_and_b32 s28, s61, 0x7fffffff
	s_max_u32 s25, s25, s28
	s_and_b32 s28, s62, 0x7fffffff
	s_max_u32 s25, s25, s28
	s_and_b32 s28, s63, 0x7fffffff
	s_max_u32 s25, s25, s28
	s_and_b32 s28, s64, 0x7fffffff
	s_max_u32 s25, s25, s28
	s_and_b32 s28, s65, 0x7fffffff
	s_max_u32 s25, s25, s28
	s_and_b32 s28, s66, 0x7fffffff
	s_max_u32 s25, s25, s28
	s_and_b32 s28, s67, 0x7fffffff
	s_max_u32 s25, s25, s28
	s_load_dwordx16 s[52:67], s[18:19], 0x1c0
	s_waitcnt lgkmcnt(0)
	s_and_b32 s28, s52, 0x7fffffff
	s_max_u32 s25, s25, s28
	s_and_b32 s28, s53, 0x7fffffff
	s_max_u32 s25, s25, s28
	s_and_b32 s28, s54, 0x7fffffff
	s_max_u32 s25, s25, s28
	s_and_b32 s28, s55, 0x7fffffff
	s_max_u32 s25, s25, s28
	s_and_b32 s28, s56, 0x7fffffff
	s_max_u32 s25, s25, s28
	s_and_b32 s28, s57, 0x7fffffff
	s_max_u32 s25, s25, s28
	s_and_b32 s28, s58, 0x7fffffff
	s_max_u32 s25, s25, s28
	s_and_b32 s28, s59, 0x7fffffff
	s_max_u32 s25, s25, s28
	s_and_b32 s28, s60, 0x7fffffff
	s_max_u32 s25, s25, s28
	s_and_b32 s28, s61, 0x7fffffff
	s_max_u32 s25, s25, s28
	s_and_b32 s28, s62, 0x7fffffff
	s_max_u32 s25, s25, s28
	s_and_b32 s28, s63, 0x7fffffff
	s_max_u32 s25, s25, s28
	s_and_b32 s28, s64, 0x7fffffff
	s_max_u32 s25, s25, s28
	s_and_b32 s28, s65, 0x7fffffff
	s_max_u32 s25, s25, s28
	s_and_b32 s28, s66, 0x7fffffff
	s_max_u32 s25, s25, s28
	s_and_b32 s28, s67, 0x7fffffff
	s_max_u32 s25, s25, s28
	s_load_dwordx16 s[52:67], s[20:21], 0x0
	s_waitcnt lgkmcnt(0)
	s_and_b32 s28, s52, 0x7fffffff
	s_max_u32 s26, s26, s28
	s_and_b32 s28, s53, 0x7fffffff
	s_max_u32 s26, s26, s28
	s_and_b32 s28, s54, 0x7fffffff
	s_max_u32 s26, s26, s28
	s_and_b32 s28, s55, 0x7fffffff
	s_max_u32 s26, s26, s28
	s_and_b32 s28, s56, 0x7fffffff
	s_max_u32 s26, s26, s28
	s_and_b32 s28, s57, 0x7fffffff
	s_max_u32 s26, s26, s28
	s_and_b32 s28, s58, 0x7fffffff
	s_max_u32 s26, s26, s28
	s_and_b32 s28, s59, 0x7fffffff
	s_max_u32 s26, s26, s28
	s_and_b32 s28, s60, 0x7fffffff
	s_max_u32 s26, s26, s28
	s_and_b32 s28, s61, 0x7fffffff
	s_max_u32 s26, s26, s28
	s_and_b32 s28, s62, 0x7fffffff
	s_max_u32 s26, s26, s28
	s_and_b32 s28, s63, 0x7fffffff
	s_max_u32 s26, s26, s28
	s_and_b32 s28, s64, 0x7fffffff
	s_max_u32 s26, s26, s28
	s_and_b32 s28, s65, 0x7fffffff
	s_max_u32 s26, s26, s28
	s_and_b32 s28, s66, 0x7fffffff
	s_max_u32 s26, s26, s28
	s_and_b32 s28, s67, 0x7fffffff
	s_max_u32 s26, s26, s28
	s_load_dwordx16 s[52:67], s[20:21], 0x40
	s_waitcnt lgkmcnt(0)
; __device__ __forceinline__ void phase_attn(const Params& p, int l, unsigned char* shm) {
;   const bf16_t* qkv = (const bf16_t*)(p.ws + WS_QKV); const bf16_t* gates = (const bf16_t*)(p.ws + WS_GATES);
;   bf16_t* merged = (bf16_t*)(p.ws + WS_XN);
;   const float* lutall = (const float*)(p.ws + WS_LUT); const float* lamp = (const float*)(p.ws + WS_LAM);
;   AttnEpi E; E.park = (float*)(p.ws + WS_PARK) + (size_t)blockIdx.x * 65536; E.gsub = p.in[22] + l * 128; E.lam = lamp[2 * l]; E.oml = lamp[2 * l + 1];
	s_and_b32 s28, s52, 0x7fffffff
	s_max_u32 s26, s26, s28
	s_and_b32 s28, s53, 0x7fffffff
	s_max_u32 s26, s26, s28
	s_and_b32 s28, s54, 0x7fffffff
	s_max_u32 s26, s26, s28
	s_and_b32 s28, s55, 0x7fffffff
	s_max_u32 s26, s26, s28
	s_and_b32 s28, s56, 0x7fffffff
	s_max_u32 s26, s26, s28
	s_and_b32 s28, s57, 0x7fffffff
	s_max_u32 s26, s26, s28
	s_and_b32 s28, s58, 0x7fffffff
	s_max_u32 s26, s26, s28
	s_and_b32 s28, s59, 0x7fffffff
	s_max_u32 s26, s26, s28
	s_and_b32 s28, s60, 0x7fffffff
	s_max_u32 s26, s26, s28
	s_and_b32 s28, s61, 0x7fffffff
	s_max_u32 s26, s26, s28
	s_and_b32 s28, s62, 0x7fffffff
	s_max_u32 s26, s26, s28
	s_and_b32 s28, s63, 0x7fffffff
	s_max_u32 s26, s26, s28
	s_and_b32 s28, s64, 0x7fffffff
	s_max_u32 s26, s26, s28
	s_and_b32 s28, s65, 0x7fffffff
	s_max_u32 s26, s26, s28
	s_and_b32 s28, s66, 0x7fffffff
	s_max_u32 s26, s26, s28
	s_and_b32 s28, s67, 0x7fffffff
	s_max_u32 s26, s26, s28
	s_load_dwordx16 s[52:67], s[20:21], 0x80
	s_waitcnt lgkmcnt(0)
	s_and_b32 s28, s52, 0x7fffffff
	s_max_u32 s26, s26, s28
	s_and_b32 s28, s53, 0x7fffffff
	s_max_u32 s26, s26, s28
	s_and_b32 s28, s54, 0x7fffffff
	s_max_u32 s26, s26, s28
	s_and_b32 s28, s55, 0x7fffffff
	s_max_u32 s26, s26, s28
	s_and_b32 s28, s56, 0x7fffffff
	s_max_u32 s26, s26, s28
	s_and_b32 s28, s57, 0x7fffffff
	s_max_u32 s26, s26, s28
	s_and_b32 s28, s58, 0x7fffffff
	s_max_u32 s26, s26, s28
	s_and_b32 s28, s59, 0x7fffffff
	s_max_u32 s26, s26, s28
	s_and_b32 s28, s60, 0x7fffffff
	s_max_u32 s26, s26, s28
	s_and_b32 s28, s61, 0x7fffffff
	s_max_u32 s26, s26, s28
	s_and_b32 s28, s62, 0x7fffffff
	s_max_u32 s26, s26, s28
	s_and_b32 s28, s63, 0x7fffffff
	s_max_u32 s26, s26, s28
	s_and_b32 s28, s64, 0x7fffffff
	s_max_u32 s26, s26, s28
	s_and_b32 s28, s65, 0x7fffffff
	s_max_u32 s26, s26, s28
	s_and_b32 s28, s66, 0x7fffffff
	s_max_u32 s26, s26, s28
	s_and_b32 s28, s67, 0x7fffffff
	s_max_u32 s26, s26, s28
	s_load_dwordx16 s[52:67], s[20:21], 0xc0
	s_waitcnt lgkmcnt(0)
	s_and_b32 s28, s52, 0x7fffffff
	s_max_u32 s26, s26, s28
	s_and_b32 s28, s53, 0x7fffffff
	s_max_u32 s26, s26, s28
	s_and_b32 s28, s54, 0x7fffffff
	s_max_u32 s26, s26, s28
	s_and_b32 s28, s55, 0x7fffffff
	s_max_u32 s26, s26, s28
	s_and_b32 s28, s56, 0x7fffffff
	s_max_u32 s26, s26, s28
	s_and_b32 s28, s57, 0x7fffffff
	s_max_u32 s26, s26, s28
	s_and_b32 s28, s58, 0x7fffffff
	s_max_u32 s26, s26, s28
	s_and_b32 s28, s59, 0x7fffffff
	s_max_u32 s26, s26, s28
	s_and_b32 s28, s60, 0x7fffffff
	s_max_u32 s26, s26, s28
	s_and_b32 s28, s61, 0x7fffffff
	s_max_u32 s26, s26, s28
	s_and_b32 s28, s62, 0x7fffffff
	s_max_u32 s26, s26, s28
	s_and_b32 s28, s63, 0x7fffffff
	s_max_u32 s26, s26, s28
	s_and_b32 s28, s64, 0x7fffffff
	s_max_u32 s26, s26, s28
	s_and_b32 s28, s65, 0x7fffffff
	s_max_u32 s26, s26, s28
	s_and_b32 s28, s66, 0x7fffffff
	s_max_u32 s26, s26, s28
	s_and_b32 s28, s67, 0x7fffffff
	s_max_u32 s26, s26, s28
	s_load_dwordx16 s[52:67], s[22:23], 0x0
	s_waitcnt lgkmcnt(0)
	s_and_b32 s28, s52, 0x7fffffff
	s_max_u32 s27, s27, s28
	s_and_b32 s28, s53, 0x7fffffff
	s_max_u32 s27, s27, s28
	s_and_b32 s28, s54, 0x7fffffff
	s_max_u32 s27, s27, s28
	s_and_b32 s28, s55, 0x7fffffff
	s_max_u32 s27, s27, s28
	s_and_b32 s28, s56, 0x7fffffff
	s_max_u32 s27, s27, s28
	s_and_b32 s28, s57, 0x7fffffff
	s_max_u32 s27, s27, s28
	s_and_b32 s28, s58, 0x7fffffff
	s_max_u32 s27, s27, s28
	s_and_b32 s28, s59, 0x7fffffff
	s_max_u32 s27, s27, s28
	s_and_b32 s28, s60, 0x7fffffff
	s_max_u32 s27, s27, s28
	s_and_b32 s28, s61, 0x7fffffff
	s_max_u32 s27, s27, s28
	s_and_b32 s28, s62, 0x7fffffff
	s_max_u32 s27, s27, s28
	s_and_b32 s28, s63, 0x7fffffff
	s_max_u32 s27, s27, s28
	s_and_b32 s28, s64, 0x7fffffff
	s_max_u32 s27, s27, s28
	s_and_b32 s28, s65, 0x7fffffff
	s_max_u32 s27, s27, s28
	s_and_b32 s28, s66, 0x7fffffff
	s_max_u32 s27, s27, s28
	s_and_b32 s28, s67, 0x7fffffff
	s_max_u32 s27, s27, s28
	s_load_dwordx16 s[52:67], s[22:23], 0x40
	s_waitcnt lgkmcnt(0)
	s_and_b32 s28, s52, 0x7fffffff
	s_max_u32 s27, s27, s28
	s_and_b32 s28, s53, 0x7fffffff
	s_max_u32 s27, s27, s28
	s_and_b32 s28, s54, 0x7fffffff
	s_max_u32 s27, s27, s28
	s_and_b32 s28, s55, 0x7fffffff
	s_max_u32 s27, s27, s28
	s_and_b32 s28, s56, 0x7fffffff
	s_max_u32 s27, s27, s28
	s_and_b32 s28, s57, 0x7fffffff
	s_max_u32 s27, s27, s28
	s_and_b32 s28, s58, 0x7fffffff
	s_max_u32 s27, s27, s28
	s_and_b32 s28, s59, 0x7fffffff
	s_max_u32 s27, s27, s28
	s_and_b32 s28, s60, 0x7fffffff
	s_max_u32 s27, s27, s28
	s_and_b32 s28, s61, 0x7fffffff
	s_max_u32 s27, s27, s28
	s_and_b32 s28, s62, 0x7fffffff
	s_max_u32 s27, s27, s28
	s_and_b32 s28, s63, 0x7fffffff
	s_max_u32 s27, s27, s28
	s_and_b32 s28, s64, 0x7fffffff
	s_max_u32 s27, s27, s28
	s_and_b32 s28, s65, 0x7fffffff
	s_max_u32 s27, s27, s28
	s_and_b32 s28, s66, 0x7fffffff
	s_max_u32 s27, s27, s28
	s_and_b32 s28, s67, 0x7fffffff
	s_max_u32 s27, s27, s28
	s_load_dwordx16 s[52:67], s[22:23], 0x80
	s_waitcnt lgkmcnt(0)
; __device__ __forceinline__ void phase_attn(const Params& p, int l, unsigned char* shm) {
;   const bf16_t* qkv = (const bf16_t*)(p.ws + WS_QKV); const bf16_t* gates = (const bf16_t*)(p.ws + WS_GATES);
;   bf16_t* merged = (bf16_t*)(p.ws + WS_XN);
;   const float* lutall = (const float*)(p.ws + WS_LUT); const float* lamp = (const float*)(p.ws + WS_LAM);
;   AttnEpi E; E.park = (float*)(p.ws + WS_PARK) + (size_t)blockIdx.x * 65536; E.gsub = p.in[22] + l * 128; E.lam = lamp[2 * l]; E.oml = lamp[2 * l + 1];
	s_and_b32 s28, s52, 0x7fffffff
	s_max_u32 s27, s27, s28
	s_and_b32 s28, s53, 0x7fffffff
	s_max_u32 s27, s27, s28
	s_and_b32 s28, s54, 0x7fffffff
	s_max_u32 s27, s27, s28
	s_and_b32 s28, s55, 0x7fffffff
	s_max_u32 s27, s27, s28
	s_and_b32 s28, s56, 0x7fffffff
	s_max_u32 s27, s27, s28
	s_and_b32 s28, s57, 0x7fffffff
	s_max_u32 s27, s27, s28
	s_and_b32 s28, s58, 0x7fffffff
	s_max_u32 s27, s27, s28
	s_and_b32 s28, s59, 0x7fffffff
	s_max_u32 s27, s27, s28
	s_and_b32 s28, s60, 0x7fffffff
	s_max_u32 s27, s27, s28
	s_and_b32 s28, s61, 0x7fffffff
	s_max_u32 s27, s27, s28
	s_and_b32 s28, s62, 0x7fffffff
	s_max_u32 s27, s27, s28
	s_and_b32 s28, s63, 0x7fffffff
	s_max_u32 s27, s27, s28
	s_and_b32 s28, s64, 0x7fffffff
	s_max_u32 s27, s27, s28
	s_and_b32 s28, s65, 0x7fffffff
	s_max_u32 s27, s27, s28
	s_and_b32 s28, s66, 0x7fffffff
	s_max_u32 s27, s27, s28
	s_and_b32 s28, s67, 0x7fffffff
	s_max_u32 s27, s27, s28
	s_load_dwordx16 s[52:67], s[22:23], 0xc0
	s_waitcnt lgkmcnt(0)
	s_and_b32 s28, s52, 0x7fffffff
	s_max_u32 s27, s27, s28
	s_and_b32 s28, s53, 0x7fffffff
	s_max_u32 s27, s27, s28
	s_and_b32 s28, s54, 0x7fffffff
	s_max_u32 s27, s27, s28
	s_and_b32 s28, s55, 0x7fffffff
	s_max_u32 s27, s27, s28
	s_and_b32 s28, s56, 0x7fffffff
	s_max_u32 s27, s27, s28
	s_and_b32 s28, s57, 0x7fffffff
	s_max_u32 s27, s27, s28
	s_and_b32 s28, s58, 0x7fffffff
	s_max_u32 s27, s27, s28
	s_and_b32 s28, s59, 0x7fffffff
	s_max_u32 s27, s27, s28
	s_and_b32 s28, s60, 0x7fffffff
	s_max_u32 s27, s27, s28
	s_and_b32 s28, s61, 0x7fffffff
	s_max_u32 s27, s27, s28
	s_and_b32 s28, s62, 0x7fffffff
	s_max_u32 s27, s27, s28
	s_and_b32 s28, s63, 0x7fffffff
	s_max_u32 s27, s27, s28
	s_and_b32 s28, s64, 0x7fffffff
	s_max_u32 s27, s27, s28
	s_and_b32 s28, s65, 0x7fffffff
	s_max_u32 s27, s27, s28
	s_and_b32 s28, s66, 0x7fffffff
	s_max_u32 s27, s27, s28
	s_and_b32 s28, s67, 0x7fffffff
	s_max_u32 s27, s27, s28
	v_mov_b32_e32 v2, s24
	v_mul_f32_e32 v2, s25, v2
	v_mul_f32_e32 v2, 0x43028f5c, v2
	v_add_f32_e32 v2, 1.0, v2
	v_min_f32_e32 v2, 0x43d70000, v2
	v_mov_b32_e32 v3, s26
	v_mul_f32_e32 v3, s27, v3
	v_mul_f32_e32 v3, 0x413c5bb7, v3
	v_add_f32_e32 v3, 1.0, v3
	v_min_f32_e32 v3, 0x42480000, v3
	s_nop 0
	v_readfirstlane_b32 s28, v2
	v_readfirstlane_b32 s29, v3
	s_nop 3
	v_writelane_b32 v255, s28, 20
	v_writelane_b32 v255, s29, 21
	s_lshl_b32 s0, s12, 7
	s_ashr_i32 s1, s0, 31
	v_readlane_b32 s52, v254, 41
	s_lshl_b64 s[0:1], s[0:1], 2
	v_readlane_b32 s64, v254, 53
	v_readlane_b32 s65, v254, 54
	s_add_u32 s6, s64, s0
	s_addc_u32 s7, s65, s1
	v_readlane_b32 s13, v255, 0
	v_writelane_b32 v255, s6, 5
	v_readlane_b32 s10, v252, 47
	v_readlane_b32 s11, v252, 48
	v_writelane_b32 v255, s7, 6
	s_lshl_b32 s6, s12, 1
	s_ashr_i32 s7, s6, 31
	s_lshl_b64 s[6:7], s[6:7], 2
	s_add_u32 s6, s10, s6
	s_addc_u32 s7, s11, s7
	global_load_dwordx2 v[184:185], v1, s[6:7]
	v_readlane_b32 s53, v254, 42
	v_readlane_b32 s54, v254, 43
	v_readlane_b32 s55, v254, 44
	v_readlane_b32 s56, v254, 45
	v_readlane_b32 s57, v254, 46
	v_readlane_b32 s58, v254, 47
	v_readlane_b32 s59, v254, 48
	v_readlane_b32 s60, v254, 49
	v_readlane_b32 s61, v254, 50
	v_readlane_b32 s62, v254, 51
	v_readlane_b32 s63, v254, 52
	v_readlane_b32 s66, v254, 55
	v_readlane_b32 s67, v254, 56
	s_lshl_b32 s6, s12, 6
	v_readlane_b32 s52, v254, 25
	s_lshl_b32 s2, s12, 3
	s_ashr_i32 s7, s6, 31
	v_readlane_b32 s58, v254, 31
	v_readlane_b32 s59, v254, 32
	s_add_u32 s12, s58, s0
	v_readlane_b32 s62, v254, 35
	s_addc_u32 s13, s59, s1
	v_readlane_b32 s63, v254, 36
	s_add_u32 s42, s62, s0
	v_readlane_b32 s66, v254, 39
	s_addc_u32 s43, s63, s1
	s_lshl_b64 s[0:1], s[6:7], 2
	v_readlane_b32 s53, v254, 26
	v_readlane_b32 s67, v254, 40
	s_add_u32 s52, s66, s0
	s_addc_u32 s53, s67, s1
	v_readlane_b32 s0, v254, 16
	v_writelane_b32 v255, s2, 7
	s_mov_b32 s93, s0
	s_mov_b32 s10, s0
	v_readlane_b32 s54, v254, 27
	v_readlane_b32 s55, v254, 28
	v_readlane_b32 s56, v254, 29
	v_readlane_b32 s57, v254, 30
	v_readlane_b32 s60, v254, 33
	v_readlane_b32 s61, v254, 34
	v_readlane_b32 s64, v254, 37
	v_readlane_b32 s65, v254, 38
	v_readlane_b32 s1, v254, 17
	s_waitcnt vmcnt(0)
	v_mov_b32_e32 v186, v184
	v_mov_b32_e32 v187, v184
	s_branch .LBB0_74

; __device__ __forceinline__ void finishSM(f32x16& p0, f32x16& p1, float alpha, float& l_reg, bf16x8& pa0, bf16x8& pa1, bf16x8& pa2, bf16x8& pa3) {
; #pragma unroll
;   for (int r = 0; r < 16; ++r) p1[r] = __builtin_amdgcn_exp2f(p1[r]);
;   float ps = 0;
; #pragma unroll
;   for (int r = 0; r < 16; ++r) ps += p0[r];
; #pragma unroll
;   for (int r = 0; r < 16; ++r) ps += p1[r];
;   { auto rr = __builtin_amdgcn_permlane32_swap(__float_as_uint(ps), __float_as_uint(ps), false, false);
;     ps = __uint_as_float(rr[0]) + __uint_as_float(rr[1]); }
;   l_reg = l_reg * alpha + ps;
;     ...
;   PK4(p0, 0, pa0); PK4(p0, 8, pa1); PK4(p1, 0, pa2); PK4(p1, 8, pa3);
;     ...
; }
; template <int ND0, int DOFF>
; __device__ __forceinline__ void qkt(f32x16& p0, f32x16& p1, const char* Ks, const bf16x8* qr, int r32, int hi) {
;   p0 = f32x16{}; p1 = f32x16{};
; #pragma unroll
;   for (int d0 = 0; d0 < ND0; ++d0) { const int cb = ((d0 + DOFF) * 16 + hi * 8) * 2;
;     bf16x8 b0 = *reinterpret_cast<const bf16x8*>(Ks + KSWZ(r32, cb));
;     bf16x8 b1 = *reinterpret_cast<const bf16x8*>(Ks + KSWZ(32 + r32, cb));
;     p0 = __builtin_amdgcn_mfma_f32_32x32x16_bf16(b0, qr[d0], p0, 0, 0, 0);
;     p1 = __builtin_amdgcn_mfma_f32_32x32x16_bf16(b1, qr[d0], p1, 0, 0, 0); }
; }
.LBB0_79:
	s_mov_b32 s69, s0
	s_waitcnt lgkmcnt(0)
	s_barrier
	s_add_i32 s0, s71, 0
	v_add_u32_e32 v70, s0, v214
	ds_read_b128 v[66:69], v70 offset:49152
	ds_read_b128 v[70:73], v70 offset:57344
	v_add_u32_e32 v162, s0, v218
	ds_read_b128 v[230:233], v162 offset:49152
	ds_read_b128 v[234:237], v162 offset:57344
	v_add_u32_e32 v162, s0, v219
	s_waitcnt lgkmcnt(3)
	v_mfma_f32_32x32x16_bf16 v[82:97], v[66:69], v[114:117], 0
	v_exp_f32_e32 v160, v160
	v_exp_f32_e32 v161, v161
	v_exp_f32_e32 v158, v158
	v_exp_f32_e32 v159, v159
	v_exp_f32_e32 v156, v156
	v_exp_f32_e32 v157, v157
	v_exp_f32_e32 v154, v154
	s_waitcnt lgkmcnt(2)
	v_mfma_f32_32x32x16_bf16 v[66:81], v[70:73], v[114:117], 0
	v_exp_f32_e32 v155, v155
	v_exp_f32_e32 v152, v152
	v_exp_f32_e32 v153, v153
	v_exp_f32_e32 v150, v150
	v_exp_f32_e32 v151, v151
	v_exp_f32_e32 v148, v148
	v_exp_f32_e32 v149, v149
	s_waitcnt lgkmcnt(1)
	v_mfma_f32_32x32x16_bf16 v[82:97], v[230:233], v[126:129], v[82:97]
	v_exp_f32_e32 v146, v146
	v_exp_f32_e32 v147, v147
	v_cvt_pk_bf16_f32 v163, v175, v177
	v_cvt_pk_bf16_f32 v229, v172, v174
	s_waitcnt lgkmcnt(0)
	v_mfma_f32_32x32x16_bf16 v[66:81], v[234:237], v[126:129], v[66:81]
	ds_read_b128 v[230:233], v162 offset:49152
	ds_read_b128 v[234:237], v162 offset:57344
	v_add_u32_e32 v162, s0, v216
	s_waitcnt lgkmcnt(1)
	v_mfma_f32_32x32x16_bf16 v[82:97], v[230:233], v[118:121], v[82:97]
	s_waitcnt lgkmcnt(0)
	v_mfma_f32_32x32x16_bf16 v[66:81], v[234:237], v[118:121], v[66:81]
	ds_read_b128 v[230:233], v162 offset:49152
	ds_read_b128 v[234:237], v162 offset:57344
	v_add_u32_e32 v162, s0, v217
	s_waitcnt lgkmcnt(1)
	v_mfma_f32_32x32x16_bf16 v[82:97], v[230:233], v[122:125], v[82:97]
	s_waitcnt lgkmcnt(0)
	v_mfma_f32_32x32x16_bf16 v[66:81], v[234:237], v[122:125], v[66:81]
	ds_read_b128 v[230:233], v162 offset:49152
	ds_read_b128 v[234:237], v162 offset:57344
	v_add_u32_e32 v162, s0, v215
	s_waitcnt lgkmcnt(1)
	v_mfma_f32_32x32x16_bf16 v[82:97], v[230:233], v[110:113], v[82:97]
	s_waitcnt lgkmcnt(0)
	v_mfma_f32_32x32x16_bf16 v[66:81], v[234:237], v[110:113], v[66:81]
	ds_read_b128 v[230:233], v162 offset:49152
	ds_read_b128 v[234:237], v162 offset:57344
	v_add_u32_e32 v162, s0, v220
	s_waitcnt lgkmcnt(1)
	v_mfma_f32_32x32x16_bf16 v[82:97], v[230:233], v[106:109], v[82:97]
	s_waitcnt lgkmcnt(0)
	v_mfma_f32_32x32x16_bf16 v[66:81], v[234:237], v[106:109], v[66:81]
	ds_read_b128 v[230:233], v162 offset:49152
	ds_read_b128 v[234:237], v162 offset:57344
	v_add_u32_e32 v162, s0, v221
	s_waitcnt lgkmcnt(1)
	v_mfma_f32_32x32x16_bf16 v[82:97], v[230:233], v[102:105], v[82:97]
	s_waitcnt lgkmcnt(0)
	v_mfma_f32_32x32x16_bf16 v[66:81], v[234:237], v[102:105], v[66:81]
	ds_read_b128 v[230:233], v162 offset:49152
	ds_read_b128 v[234:237], v162 offset:57344
	v_add_f32_e32 v162, v165, v164
	v_add_f32_e32 v162, v175, v162
	v_add_f32_e32 v162, v177, v162
	v_add_f32_e32 v162, v227, v162
	v_add_f32_e32 v162, v228, v162
	v_add_f32_e32 v162, v176, v162
	v_add_f32_e32 v162, v226, v162
	v_add_f32_e32 v162, v167, v162
	v_add_f32_e32 v162, v169, v162
	v_add_f32_e32 v162, v171, v162
	v_add_f32_e32 v162, v173, v162
	v_add_f32_e32 v162, v168, v162
	v_add_f32_e32 v162, v170, v162
	v_add_f32_e32 v162, v172, v162
	v_add_f32_e32 v162, v174, v162
	v_add_f32_e32 v162, v160, v162
	v_add_f32_e32 v162, v161, v162
	v_add_f32_e32 v162, v158, v162
	v_add_f32_e32 v162, v159, v162
	v_add_f32_e32 v162, v156, v162
	v_add_f32_e32 v162, v157, v162
	v_add_f32_e32 v162, v154, v162
	v_add_f32_e32 v162, v155, v162
	v_add_f32_e32 v162, v152, v162
	v_add_f32_e32 v162, v153, v162
	s_waitcnt lgkmcnt(1)
	v_mfma_f32_32x32x16_bf16 v[82:97], v[230:233], v[98:101], v[82:97]
	v_add_f32_e32 v162, v150, v162
	v_add_f32_e32 v162, v151, v162
	v_add_f32_e32 v162, v148, v162
	v_add_f32_e32 v162, v149, v162
	v_add_f32_e32 v162, v146, v162
	v_add_f32_e32 v223, v147, v162
	v_mov_b32_e32 v224, v223
	s_waitcnt lgkmcnt(0)
; #define SBAR() __builtin_amdgcn_sched_barrier(0)
; __device__ __forceinline__ void finishSM(f32x16& p0, f32x16& p1, float alpha, float& l_reg, bf16x8& pa0, bf16x8& pa1, bf16x8& pa2, bf16x8& pa3) {
;     ...
;   { auto rr = __builtin_amdgcn_permlane32_swap(__float_as_uint(ps), __float_as_uint(ps), false, false);
;     ps = __uint_as_float(rr[0]) + __uint_as_float(rr[1]); }
;   l_reg = l_reg * alpha + ps;
;     ...
;   PK4(p0, 0, pa0); PK4(p0, 8, pa1); PK4(p1, 0, pa2); PK4(p1, 8, pa3);
;     ...
; }
; template <int ND0, int DOFF>
; __device__ __forceinline__ void qkt(f32x16& p0, f32x16& p1, const char* Ks, const bf16x8* qr, int r32, int hi) {
;   p0 = f32x16{}; p1 = f32x16{};
; #pragma unroll
;   for (int d0 = 0; d0 < ND0; ++d0) { const int cb = ((d0 + DOFF) * 16 + hi * 8) * 2;
;     bf16x8 b0 = *reinterpret_cast<const bf16x8*>(Ks + KSWZ(r32, cb));
;     bf16x8 b1 = *reinterpret_cast<const bf16x8*>(Ks + KSWZ(32 + r32, cb));
;     p0 = __builtin_amdgcn_mfma_f32_32x32x16_bf16(b0, qr[d0], p0, 0, 0, 0);
;     p1 = __builtin_amdgcn_mfma_f32_32x32x16_bf16(b1, qr[d0], p1, 0, 0, 0); }
; }
; __device__ __forceinline__ int v_st(int k, int c) { const int kk = (k & ~0xC) | ((k & 4) << 1) | ((k & 8) >> 1); return ((kk >> 3) * 4 + (c >> 5)) * 512 + ((kk & 7) * 32 + (c & 31)) * 2; }
; __device__ __forceinline__ int v_rd_base(int lane) { return ((lane & 3) << 3) | (((lane >> 2) & 3) << 6) | (((lane >> 4) & 1) << 5) | (((lane >> 5) & 1) << 8); }
; template <int OFF> __device__ __forceinline__ s16x4 tr_read(int vb) {
;   s16x4 r; asm volatile("ds_read_b64_tr_b16 %0, %1 offset:%2" : "=&v"(r) : "v"(vb), "i"(OFF) : "memory"); return r;
; }
; template <int D0> __device__ __forceinline__ void pv_one(f32x16& od, int vb, bf16x8 pa0, bf16x8 pa1, bf16x8 pa2, bf16x8 pa3) {
;   const s16x4 l0 = tr_read<v_rd_off(D0, 0, 0)>(vb), h0 = tr_read<v_rd_off(D0, 0, 1)>(vb), l1 = tr_read<v_rd_off(D0, 1, 0)>(vb), h1 = tr_read<v_rd_off(D0, 1, 1)>(vb);
;   const s16x4 l2 = tr_read<v_rd_off(D0, 2, 0)>(vb), h2 = tr_read<v_rd_off(D0, 2, 1)>(vb), l3 = tr_read<v_rd_off(D0, 3, 0)>(vb), h3 = tr_read<v_rd_off(D0, 3, 1)>(vb);
;   asm volatile("s_waitcnt lgkmcnt(0)" ::: "memory"); SBAR();
;     ...
;   od = __builtin_amdgcn_mfma_f32_32x32x16_bf16(pa0, PK(l0, h0), od, 0, 0, 0);
;   od = __builtin_amdgcn_mfma_f32_32x32x16_bf16(pa1, PK(l1, h1), od, 0, 0, 0);
;   od = __builtin_amdgcn_mfma_f32_32x32x16_bf16(pa2, PK(l2, h2), od, 0, 0, 0);
	v_mfma_f32_32x32x16_bf16 v[66:81], v[234:237], v[98:101], v[66:81]
	v_cvt_pk_bf16_f32 v162, v164, v165
	v_cvt_pk_bf16_f32 v164, v227, v228
	v_permlane32_swap_b32_e32 v223, v224
	v_cvt_pk_bf16_f32 v165, v176, v226
	v_permlane32_swap_b32_e32 v162, v164
	v_cvt_pk_bf16_f32 v226, v167, v169
	v_cvt_pk_bf16_f32 v227, v171, v173
	v_cvt_pk_bf16_f32 v228, v168, v170
	v_cvt_pk_bf16_f32 v168, v160, v161
	v_cvt_pk_bf16_f32 v169, v158, v159
	v_cvt_pk_bf16_f32 v170, v156, v157
	v_cvt_pk_bf16_f32 v171, v154, v155
	v_cvt_pk_bf16_f32 v172, v152, v153
	v_cvt_pk_bf16_f32 v173, v150, v151
	v_cvt_pk_bf16_f32 v174, v148, v149
	v_cvt_pk_bf16_f32 v175, v146, v147
	v_permlane32_swap_b32_e32 v163, v165
	v_permlane32_swap_b32_e32 v226, v228
	v_permlane32_swap_b32_e32 v227, v229
	v_permlane32_swap_b32_e32 v168, v170
	v_permlane32_swap_b32_e32 v169, v171
	v_permlane32_swap_b32_e32 v172, v174
	v_permlane32_swap_b32_e32 v173, v175
	v_add_co_u32_e32 v150, vcc, s4, v190
	s_nop 1
	v_addc_co_u32_e32 v151, vcc, -1, v191, vcc
	v_add_co_u32_e32 v154, vcc, s5, v190
	s_nop 1
	v_addc_co_u32_e32 v155, vcc, -1, v191, vcc
	global_load_dwordx4 v[146:149], v[150:151], off
	s_nop 0
	global_load_dwordx4 v[150:153], v[150:151], off offset:-512
	s_nop 0
	global_load_dwordx4 v[158:161], v[154:155], off
	s_nop 0
	global_load_dwordx4 v[154:157], v[154:155], off offset:-512
	v_add_u32_e32 v208, s68, v209
	ds_read_b64_tr_b16 v[230:231], v208 offset:0
	ds_read_b64_tr_b16 v[232:233], v208 offset:0x800
	ds_read_b64_tr_b16 v[234:235], v208 offset:0x1000
	ds_read_b64_tr_b16 v[236:237], v208 offset:0x1800
	ds_read_b64_tr_b16 v[238:239], v208 offset:0x2000
	ds_read_b64_tr_b16 v[240:241], v208 offset:0x2800
	ds_read_b64_tr_b16 v[242:243], v208 offset:0x3000
	ds_read_b64_tr_b16 v[244:245], v208 offset:0x3800
	s_waitcnt lgkmcnt(0)
	s_nop 0
	v_mfma_f32_32x32x16_bf16 v[18:33], v[162:165], v[230:233], v[18:33]
	ds_read_b64_tr_b16 v[230:231], v208 offset:0x200
	ds_read_b64_tr_b16 v[232:233], v208 offset:0xa00
	v_mfma_f32_32x32x16_bf16 v[18:33], v[226:229], v[234:237], v[18:33]
	ds_read_b64_tr_b16 v[234:235], v208 offset:0x1200
	ds_read_b64_tr_b16 v[236:237], v208 offset:0x1a00
	v_mfma_f32_32x32x16_bf16 v[18:33], v[168:171], v[238:241], v[18:33]
	ds_read_b64_tr_b16 v[238:239], v208 offset:0x2200
	ds_read_b64_tr_b16 v[240:241], v208 offset:0x2a00
	v_mfma_f32_32x32x16_bf16 v[18:33], v[172:175], v[242:245], v[18:33]
	ds_read_b64_tr_b16 v[242:243], v208 offset:0x3200
	ds_read_b64_tr_b16 v[244:245], v208 offset:0x3a00
	s_waitcnt lgkmcnt(0)
	v_mfma_f32_32x32x16_bf16 v[50:65], v[162:165], v[230:233], v[50:65]
	ds_read_b64_tr_b16 v[230:231], v208 offset:0x400
	ds_read_b64_tr_b16 v[232:233], v208 offset:0xc00
	v_mfma_f32_32x32x16_bf16 v[50:65], v[226:229], v[234:237], v[50:65]
	ds_read_b64_tr_b16 v[234:235], v208 offset:0x1400
	ds_read_b64_tr_b16 v[236:237], v208 offset:0x1c00
	v_mfma_f32_32x32x16_bf16 v[50:65], v[168:171], v[238:241], v[50:65]
	ds_read_b64_tr_b16 v[238:239], v208 offset:0x2400
	ds_read_b64_tr_b16 v[240:241], v208 offset:0x2c00
	v_mfma_f32_32x32x16_bf16 v[50:65], v[172:175], v[242:245], v[50:65]
	ds_read_b64_tr_b16 v[242:243], v208 offset:0x3400
	ds_read_b64_tr_b16 v[244:245], v208 offset:0x3c00
	s_waitcnt lgkmcnt(0)
	v_mfma_f32_32x32x16_bf16 v[34:49], v[162:165], v[230:233], v[34:49]
	ds_read_b64_tr_b16 v[230:231], v208 offset:0x600
	ds_read_b64_tr_b16 v[232:233], v208 offset:0xe00
	v_mfma_f32_32x32x16_bf16 v[34:49], v[226:229], v[234:237], v[34:49]
	ds_read_b64_tr_b16 v[234:235], v208 offset:0x1600
	ds_read_b64_tr_b16 v[236:237], v208 offset:0x1e00
	v_mfma_f32_32x32x16_bf16 v[34:49], v[168:171], v[238:241], v[34:49]
	ds_read_b64_tr_b16 v[238:239], v208 offset:0x2600
	ds_read_b64_tr_b16 v[240:241], v208 offset:0x2e00
	v_mfma_f32_32x32x16_bf16 v[34:49], v[172:175], v[242:245], v[34:49]
	ds_read_b64_tr_b16 v[242:243], v208 offset:0x3600
	ds_read_b64_tr_b16 v[244:245], v208 offset:0x3e00
	s_waitcnt lgkmcnt(0)
	v_mfma_f32_32x32x16_bf16 v[2:17], v[162:165], v[230:233], v[2:17]
	v_mfma_f32_32x32x16_bf16 v[2:17], v[226:229], v[234:237], v[2:17]
	v_mfma_f32_32x32x16_bf16 v[2:17], v[168:171], v[238:241], v[2:17]
	v_mfma_f32_32x32x16_bf16 v[2:17], v[172:175], v[242:245], v[2:17]
	s_add_i32 s72, s69, 0
	v_add_u32_e32 v163, s72, v210
	s_waitcnt vmcnt(4)
	s_waitcnt vmcnt(4)
	ds_write_b128 v163, v[130:133]
	ds_write_b128 v163, v[138:141] offset:8192
	v_add_u32_e32 v163, s72, v212
	ds_write_b128 v163, v[142:145] offset:49152
	ds_write_b128 v163, v[134:137] offset:57344

; #define SBAR() __builtin_amdgcn_sched_barrier(0)
; template <int D0> __device__ __forceinline__ void pv_one(f32x16& od, int vb, bf16x8 pa0, bf16x8 pa1, bf16x8 pa2, bf16x8 pa3) {
;   const s16x4 l0 = tr_read<v_rd_off(D0, 0, 0)>(vb), h0 = tr_read<v_rd_off(D0, 0, 1)>(vb), l1 = tr_read<v_rd_off(D0, 1, 0)>(vb), h1 = tr_read<v_rd_off(D0, 1, 1)>(vb);
;   const s16x4 l2 = tr_read<v_rd_off(D0, 2, 0)>(vb), h2 = tr_read<v_rd_off(D0, 2, 1)>(vb), l3 = tr_read<v_rd_off(D0, 3, 0)>(vb), h3 = tr_read<v_rd_off(D0, 3, 1)>(vb);
;   asm volatile("s_waitcnt lgkmcnt(0)" ::: "memory"); SBAR();
;     ...
;   od = __builtin_amdgcn_mfma_f32_32x32x16_bf16(pa0, PK(l0, h0), od, 0, 0, 0);
;   od = __builtin_amdgcn_mfma_f32_32x32x16_bf16(pa1, PK(l1, h1), od, 0, 0, 0);
;   od = __builtin_amdgcn_mfma_f32_32x32x16_bf16(pa2, PK(l2, h2), od, 0, 0, 0);
;   od = __builtin_amdgcn_mfma_f32_32x32x16_bf16(pa3, PK(l3, h3), od, 0, 0, 0);
;     ...
; }
; __device__ __forceinline__ void pv_d0(f32x16* o, int vb, bf16x8 pa0, bf16x8 pa1, bf16x8 pa2, bf16x8 pa3) {
;   pv_one<0>(o[0], vb, pa0, pa1, pa2, pa3); pv_one<1>(o[1], vb, pa0, pa1, pa2, pa3); pv_one<2>(o[2], vb, pa0, pa1, pa2, pa3); pv_one<3>(o[3], vb, pa0, pa1, pa2, pa3);
.LBB0_85:
	v_add_u32_e32 v194, s71, v209
	ds_read_b64_tr_b16 v[232:233], v194 offset:0
	ds_read_b64_tr_b16 v[234:235], v194 offset:0x800
	ds_read_b64_tr_b16 v[236:237], v194 offset:0x1000
	ds_read_b64_tr_b16 v[238:239], v194 offset:0x1800
	ds_read_b64_tr_b16 v[240:241], v194 offset:0x2000
	ds_read_b64_tr_b16 v[242:243], v194 offset:0x2800
	ds_read_b64_tr_b16 v[244:245], v194 offset:0x3000
	ds_read_b64_tr_b16 v[246:247], v194 offset:0x3800
	s_waitcnt lgkmcnt(0)
	s_nop 0
	v_mfma_f32_32x32x16_bf16 v[18:33], v[162:165], v[232:235], v[18:33]
	ds_read_b64_tr_b16 v[232:233], v194 offset:0x200
	ds_read_b64_tr_b16 v[234:235], v194 offset:0xa00
	v_mfma_f32_32x32x16_bf16 v[18:33], v[166:169], v[236:239], v[18:33]
	ds_read_b64_tr_b16 v[236:237], v194 offset:0x1200
	ds_read_b64_tr_b16 v[238:239], v194 offset:0x1a00
	v_mfma_f32_32x32x16_bf16 v[18:33], v[170:173], v[240:243], v[18:33]
	ds_read_b64_tr_b16 v[240:241], v194 offset:0x2200
	ds_read_b64_tr_b16 v[242:243], v194 offset:0x2a00
	v_mfma_f32_32x32x16_bf16 v[18:33], v[174:177], v[244:247], v[18:33]
	ds_read_b64_tr_b16 v[244:245], v194 offset:0x3200
	ds_read_b64_tr_b16 v[246:247], v194 offset:0x3a00
	s_waitcnt lgkmcnt(0)
	v_mfma_f32_32x32x16_bf16 v[50:65], v[162:165], v[232:235], v[50:65]
	ds_read_b64_tr_b16 v[232:233], v194 offset:0x400
	ds_read_b64_tr_b16 v[234:235], v194 offset:0xc00
	v_mfma_f32_32x32x16_bf16 v[50:65], v[166:169], v[236:239], v[50:65]
	ds_read_b64_tr_b16 v[236:237], v194 offset:0x1400
	ds_read_b64_tr_b16 v[238:239], v194 offset:0x1c00
	v_mfma_f32_32x32x16_bf16 v[50:65], v[170:173], v[240:243], v[50:65]
	ds_read_b64_tr_b16 v[240:241], v194 offset:0x2400
	ds_read_b64_tr_b16 v[242:243], v194 offset:0x2c00
	v_mfma_f32_32x32x16_bf16 v[50:65], v[174:177], v[244:247], v[50:65]
	ds_read_b64_tr_b16 v[244:245], v194 offset:0x3400
	ds_read_b64_tr_b16 v[246:247], v194 offset:0x3c00
	s_waitcnt lgkmcnt(0)
	v_mfma_f32_32x32x16_bf16 v[34:49], v[162:165], v[232:235], v[34:49]
	ds_read_b64_tr_b16 v[232:233], v194 offset:0x600
	ds_read_b64_tr_b16 v[234:235], v194 offset:0xe00
	v_mfma_f32_32x32x16_bf16 v[34:49], v[166:169], v[236:239], v[34:49]
	ds_read_b64_tr_b16 v[236:237], v194 offset:0x1600
	ds_read_b64_tr_b16 v[238:239], v194 offset:0x1e00
	v_mfma_f32_32x32x16_bf16 v[34:49], v[170:173], v[240:243], v[34:49]
	ds_read_b64_tr_b16 v[240:241], v194 offset:0x2600
	ds_read_b64_tr_b16 v[242:243], v194 offset:0x2e00
	v_mfma_f32_32x32x16_bf16 v[34:49], v[174:177], v[244:247], v[34:49]
	ds_read_b64_tr_b16 v[244:245], v194 offset:0x3600
	ds_read_b64_tr_b16 v[246:247], v194 offset:0x3e00
	s_waitcnt lgkmcnt(0)
	v_mfma_f32_32x32x16_bf16 v[2:17], v[162:165], v[232:235], v[2:17]
	v_mfma_f32_32x32x16_bf16 v[2:17], v[166:169], v[236:239], v[2:17]
	v_mfma_f32_32x32x16_bf16 v[2:17], v[170:173], v[240:243], v[2:17]
	v_mfma_f32_32x32x16_bf16 v[2:17], v[174:177], v[244:247], v[2:17]
	s_add_i32 s72, s68, 0
	v_add_u32_e32 v164, s72, v210
	s_waitcnt vmcnt(4)
	s_waitcnt vmcnt(3)
	ds_write_b128 v164, v[146:149]
	s_waitcnt vmcnt(1)
	ds_write_b128 v164, v[158:161] offset:8192
	v_add_u32_e32 v146, s72, v212
	ds_write_b128 v146, v[150:153] offset:49152
	s_waitcnt vmcnt(0)
	ds_write_b128 v146, v[154:157] offset:57344

.LBB0_138:
	s_or_b64 exec, exec, s[66:67]
	s_add_i32 s66, s79, 0
	v_add_u32_e32 v98, s66, v206
	s_waitcnt vmcnt(4)
	s_waitcnt vmcnt(4)
	ds_write_b128 v98, v[154:157]
	ds_write_b128 v98, v[158:161] offset:8192
	v_add_u32_e32 v98, s66, v211
	ds_write_b128 v98, v[146:149] offset:49152
	v_cmp_gt_f32_e32 vcc, 1.0, v226
	ds_write_b128 v98, v[150:153] offset:57344
	s_cbranch_vccz .LBB0_142
	s_and_saveexec_b64 s[64:65], s[6:7]
	ds_write_b32 v209, v226 offset:128
	s_or_b64 exec, exec, s[64:65]
	s_waitcnt lgkmcnt(0)
	ds_read_b128 v[98:101], v208 offset:224
	ds_read_b128 v[102:105], v208 offset:192
	ds_read_b128 v[106:109], v208 offset:160
	ds_read_b128 v[110:113], v208 offset:128
	s_waitcnt lgkmcnt(3)
	v_pk_mul_f32 v[64:65], v[64:65], v[100:101]
	s_waitcnt lgkmcnt(2)
	v_pk_mul_f32 v[60:61], v[60:61], v[104:105]
	s_waitcnt lgkmcnt(1)
	v_pk_mul_f32 v[56:57], v[56:57], v[108:109]
	s_waitcnt lgkmcnt(0)
	v_pk_mul_f32 v[52:53], v[52:53], v[112:113]
	v_pk_mul_f32 v[62:63], v[62:63], v[98:99]
	v_pk_mul_f32 v[58:59], v[58:59], v[102:103]
	v_pk_mul_f32 v[54:55], v[54:55], v[106:107]
	v_pk_mul_f32 v[50:51], v[50:51], v[110:111]
	v_pk_mul_f32 v[48:49], v[48:49], v[100:101]
	v_pk_mul_f32 v[44:45], v[44:45], v[104:105]
	v_pk_mul_f32 v[40:41], v[40:41], v[108:109]
	v_pk_mul_f32 v[36:37], v[36:37], v[112:113]
	v_pk_mul_f32 v[46:47], v[46:47], v[98:99]
	v_pk_mul_f32 v[42:43], v[42:43], v[102:103]
	v_pk_mul_f32 v[38:39], v[38:39], v[106:107]
	v_pk_mul_f32 v[34:35], v[34:35], v[110:111]
	v_pk_mul_f32 v[32:33], v[32:33], v[100:101]
	v_pk_mul_f32 v[28:29], v[28:29], v[104:105]
	v_pk_mul_f32 v[24:25], v[24:25], v[108:109]
	v_pk_mul_f32 v[20:21], v[20:21], v[112:113]
	v_pk_mul_f32 v[30:31], v[30:31], v[98:99]
	v_pk_mul_f32 v[26:27], v[26:27], v[102:103]
	v_pk_mul_f32 v[22:23], v[22:23], v[106:107]
	v_pk_mul_f32 v[18:19], v[18:19], v[110:111]
	v_pk_mul_f32 v[16:17], v[16:17], v[100:101]
	v_pk_mul_f32 v[12:13], v[12:13], v[104:105]
	v_pk_mul_f32 v[8:9], v[8:9], v[108:109]
	v_pk_mul_f32 v[4:5], v[4:5], v[112:113]
	v_pk_mul_f32 v[14:15], v[14:15], v[98:99]
	v_pk_mul_f32 v[10:11], v[10:11], v[102:103]
	v_pk_mul_f32 v[6:7], v[6:7], v[106:107]
	v_pk_mul_f32 v[2:3], v[2:3], v[110:111]

.LBB0_150:
	s_or_b64 exec, exec, s[68:69]
	s_add_i32 s68, s80, 0
	v_add_u32_e32 v98, s68, v206
	s_waitcnt vmcnt(4)
	s_waitcnt vmcnt(3)
	ds_write_b128 v98, v[162:165]
	s_waitcnt vmcnt(1)
	ds_write_b128 v98, v[174:177] offset:8192
	v_add_u32_e32 v98, s68, v211
	ds_write_b128 v98, v[166:169] offset:49152
	v_cmp_gt_f32_e32 vcc, 1.0, v225
	s_waitcnt vmcnt(0)
	ds_write_b128 v98, v[170:173] offset:57344
	s_cbranch_vccz .LBB0_154
	s_and_saveexec_b64 s[66:67], s[6:7]
	ds_write_b32 v209, v225 offset:128
	s_or_b64 exec, exec, s[66:67]
	s_waitcnt lgkmcnt(0)
	ds_read_b128 v[98:101], v208 offset:224
	ds_read_b128 v[102:105], v208 offset:192
	ds_read_b128 v[106:109], v208 offset:160
	ds_read_b128 v[110:113], v208 offset:128
	s_waitcnt lgkmcnt(3)
	v_pk_mul_f32 v[64:65], v[64:65], v[100:101]
	s_waitcnt lgkmcnt(2)
	v_pk_mul_f32 v[60:61], v[60:61], v[104:105]
	s_waitcnt lgkmcnt(1)
	v_pk_mul_f32 v[56:57], v[56:57], v[108:109]
	s_waitcnt lgkmcnt(0)
	v_pk_mul_f32 v[52:53], v[52:53], v[112:113]
	v_pk_mul_f32 v[62:63], v[62:63], v[98:99]
	v_pk_mul_f32 v[58:59], v[58:59], v[102:103]
	v_pk_mul_f32 v[54:55], v[54:55], v[106:107]
	v_pk_mul_f32 v[50:51], v[50:51], v[110:111]
	v_pk_mul_f32 v[48:49], v[48:49], v[100:101]
	v_pk_mul_f32 v[44:45], v[44:45], v[104:105]
	v_pk_mul_f32 v[40:41], v[40:41], v[108:109]
	v_pk_mul_f32 v[36:37], v[36:37], v[112:113]
	v_pk_mul_f32 v[46:47], v[46:47], v[98:99]
	v_pk_mul_f32 v[42:43], v[42:43], v[102:103]
	v_pk_mul_f32 v[38:39], v[38:39], v[106:107]
	v_pk_mul_f32 v[34:35], v[34:35], v[110:111]
	v_pk_mul_f32 v[32:33], v[32:33], v[100:101]
	v_pk_mul_f32 v[28:29], v[28:29], v[104:105]
	v_pk_mul_f32 v[24:25], v[24:25], v[108:109]
	v_pk_mul_f32 v[20:21], v[20:21], v[112:113]
	v_pk_mul_f32 v[30:31], v[30:31], v[98:99]
	v_pk_mul_f32 v[26:27], v[26:27], v[102:103]
	v_pk_mul_f32 v[22:23], v[22:23], v[106:107]
	v_pk_mul_f32 v[18:19], v[18:19], v[110:111]
	v_pk_mul_f32 v[16:17], v[16:17], v[100:101]
	v_pk_mul_f32 v[12:13], v[12:13], v[104:105]
	v_pk_mul_f32 v[8:9], v[8:9], v[108:109]
	v_pk_mul_f32 v[4:5], v[4:5], v[112:113]
	v_pk_mul_f32 v[14:15], v[14:15], v[98:99]
	v_pk_mul_f32 v[10:11], v[10:11], v[102:103]
	v_pk_mul_f32 v[6:7], v[6:7], v[106:107]
	v_pk_mul_f32 v[2:3], v[2:3], v[110:111]

.LBB0_183:
	s_or_b64 exec, exec, s[58:59]
	s_add_i32 s58, s2, 0
	v_add_u32_e32 v98, s58, v209
	s_waitcnt vmcnt(4)
	s_waitcnt vmcnt(4)
	ds_write_b128 v98, v[154:157]
	ds_write_b128 v98, v[158:161] offset:8192
	v_add_u32_e32 v98, s58, v214
	ds_write_b128 v98, v[146:149] offset:49152
	v_cmp_gt_f32_e32 vcc, 1.0, v229
	ds_write_b128 v98, v[150:153] offset:57344
	s_cbranch_vccz .LBB0_187
	s_and_saveexec_b64 s[0:1], s[6:7]
	ds_write_b32 v212, v229 offset:128
	s_or_b64 exec, exec, s[0:1]
	s_waitcnt lgkmcnt(0)
	ds_read_b128 v[98:101], v210 offset:224
	ds_read_b128 v[102:105], v210 offset:192
	ds_read_b128 v[106:109], v210 offset:160
	ds_read_b128 v[110:113], v210 offset:128
	s_waitcnt lgkmcnt(3)
	v_pk_mul_f32 v[64:65], v[64:65], v[100:101]
	s_waitcnt lgkmcnt(2)
	v_pk_mul_f32 v[60:61], v[60:61], v[104:105]
	s_waitcnt lgkmcnt(1)
	v_pk_mul_f32 v[56:57], v[56:57], v[108:109]
	s_waitcnt lgkmcnt(0)
	v_pk_mul_f32 v[52:53], v[52:53], v[112:113]
	v_pk_mul_f32 v[62:63], v[62:63], v[98:99]
	v_pk_mul_f32 v[58:59], v[58:59], v[102:103]
	v_pk_mul_f32 v[54:55], v[54:55], v[106:107]
	v_pk_mul_f32 v[50:51], v[50:51], v[110:111]
	v_pk_mul_f32 v[48:49], v[48:49], v[100:101]
	v_pk_mul_f32 v[44:45], v[44:45], v[104:105]
	v_pk_mul_f32 v[40:41], v[40:41], v[108:109]
	v_pk_mul_f32 v[36:37], v[36:37], v[112:113]
	v_pk_mul_f32 v[46:47], v[46:47], v[98:99]
	v_pk_mul_f32 v[42:43], v[42:43], v[102:103]
	v_pk_mul_f32 v[38:39], v[38:39], v[106:107]
	v_pk_mul_f32 v[34:35], v[34:35], v[110:111]
	v_pk_mul_f32 v[32:33], v[32:33], v[100:101]
	v_pk_mul_f32 v[28:29], v[28:29], v[104:105]
	v_pk_mul_f32 v[24:25], v[24:25], v[108:109]
	v_pk_mul_f32 v[20:21], v[20:21], v[112:113]
	v_pk_mul_f32 v[30:31], v[30:31], v[98:99]
	v_pk_mul_f32 v[26:27], v[26:27], v[102:103]
	v_pk_mul_f32 v[22:23], v[22:23], v[106:107]
	v_pk_mul_f32 v[18:19], v[18:19], v[110:111]
	v_pk_mul_f32 v[16:17], v[16:17], v[100:101]
	v_pk_mul_f32 v[12:13], v[12:13], v[104:105]
	v_pk_mul_f32 v[8:9], v[8:9], v[108:109]
	v_pk_mul_f32 v[4:5], v[4:5], v[112:113]
	v_pk_mul_f32 v[14:15], v[14:15], v[98:99]
	v_pk_mul_f32 v[10:11], v[10:11], v[102:103]
	v_pk_mul_f32 v[6:7], v[6:7], v[106:107]
	v_pk_mul_f32 v[2:3], v[2:3], v[110:111]

.LBB0_195:
	s_or_b64 exec, exec, s[60:61]
	s_add_i32 s60, s66, 0
	v_add_u32_e32 v98, s60, v209
	s_waitcnt vmcnt(4)
	s_waitcnt vmcnt(3)
	ds_write_b128 v98, v[162:165]
	s_waitcnt vmcnt(1)
	ds_write_b128 v98, v[174:177] offset:8192
	v_add_u32_e32 v98, s60, v214
	ds_write_b128 v98, v[166:169] offset:49152
	v_cmp_gt_f32_e32 vcc, 1.0, v228
	s_waitcnt vmcnt(0)
	ds_write_b128 v98, v[170:173] offset:57344
	s_cbranch_vccz .LBB0_199
	s_and_saveexec_b64 s[58:59], s[6:7]
	ds_write_b32 v212, v228 offset:128
	s_or_b64 exec, exec, s[58:59]
	s_waitcnt lgkmcnt(0)
	ds_read_b128 v[98:101], v210 offset:224
	ds_read_b128 v[102:105], v210 offset:192
	ds_read_b128 v[106:109], v210 offset:160
	ds_read_b128 v[110:113], v210 offset:128
	s_waitcnt lgkmcnt(3)
	v_pk_mul_f32 v[64:65], v[64:65], v[100:101]
	s_waitcnt lgkmcnt(2)
	v_pk_mul_f32 v[60:61], v[60:61], v[104:105]
	s_waitcnt lgkmcnt(1)
	v_pk_mul_f32 v[56:57], v[56:57], v[108:109]
	s_waitcnt lgkmcnt(0)
	v_pk_mul_f32 v[52:53], v[52:53], v[112:113]
	v_pk_mul_f32 v[62:63], v[62:63], v[98:99]
	v_pk_mul_f32 v[58:59], v[58:59], v[102:103]
	v_pk_mul_f32 v[54:55], v[54:55], v[106:107]
	v_pk_mul_f32 v[50:51], v[50:51], v[110:111]
	v_pk_mul_f32 v[48:49], v[48:49], v[100:101]
	v_pk_mul_f32 v[44:45], v[44:45], v[104:105]
	v_pk_mul_f32 v[40:41], v[40:41], v[108:109]
	v_pk_mul_f32 v[36:37], v[36:37], v[112:113]
	v_pk_mul_f32 v[46:47], v[46:47], v[98:99]
	v_pk_mul_f32 v[42:43], v[42:43], v[102:103]
	v_pk_mul_f32 v[38:39], v[38:39], v[106:107]
	v_pk_mul_f32 v[34:35], v[34:35], v[110:111]
	v_pk_mul_f32 v[32:33], v[32:33], v[100:101]
	v_pk_mul_f32 v[28:29], v[28:29], v[104:105]
	v_pk_mul_f32 v[24:25], v[24:25], v[108:109]
	v_pk_mul_f32 v[20:21], v[20:21], v[112:113]
	v_pk_mul_f32 v[30:31], v[30:31], v[98:99]
	v_pk_mul_f32 v[26:27], v[26:27], v[102:103]
	v_pk_mul_f32 v[22:23], v[22:23], v[106:107]
	v_pk_mul_f32 v[18:19], v[18:19], v[110:111]
	v_pk_mul_f32 v[16:17], v[16:17], v[100:101]
	v_pk_mul_f32 v[12:13], v[12:13], v[104:105]
	v_pk_mul_f32 v[8:9], v[8:9], v[108:109]
	v_pk_mul_f32 v[4:5], v[4:5], v[112:113]
	v_pk_mul_f32 v[14:15], v[14:15], v[98:99]
	v_pk_mul_f32 v[10:11], v[10:11], v[102:103]
	v_pk_mul_f32 v[6:7], v[6:7], v[106:107]
	v_pk_mul_f32 v[2:3], v[2:3], v[110:111]
